# v11 + attention key-block loop: wave-uniform test (v_cndmask + v_cmp_ne) replaced by one s_andn2_b64 (strategy 7.12)
# baseline (speedup 1.0000x reference)
; __device__ __forceinline__ unsigned cvt_pk_bf16(float lo, float hi) { unsigned r; asm volatile("v_cvt_pk_bf16_f32 %0, %1, %2" : "=v"(r) : "v"(lo), "v"(hi)); return r; }
; #define LAS __attribute__((address_space(3)))
; __device__ __forceinline__ unsigned cvt_pk_bf16(float lo, float hi) { f32x2_t v = {lo, hi}; bf16x2_t b = __builtin_convertvector(v, bf16x2_t); return __builtin_bit_cast(unsigned, b); }
; __device__ __forceinline__ float fexp(float x) { return __builtin_amdgcn_exp2f(1.4426950408889634f * x); }
; #define MMA16(b, a, c) __builtin_amdgcn_mfma_f32_16x16x32_bf16((b), (a), (c), 0, 0, 0)
; __device__ __forceinline__ void attn_phase(const Params& p, LAS unsigned char* lds, int G) {
;     ...
;             for (int m = 0; m < 4; ++m) {
;                 f32x4 s[4];
; #pragma unroll
;                 for (int n = 0; n < 4; ++n) { f32x4 a = (f32x4){0.f, 0.f, 0.f, 0.f}; a = MMA16(kf[n][0], qf[m][0], a); a = MMA16(kf[n][1], qf[m][1], a); s[n] = a; }
;                 const int i = row0 + 16 * m + fr; float mx = mrow[m];
;                 if (edge) {
; #pragma unroll
;                     for (int n = 0; n < 4; ++n)
; #pragma unroll
;                         for (int e = 0; e < 4; ++e) { const int j = kstart + 16 * n + 4 * fq + e, dlt = i - j; const bool valid = (dlt <= 128) && (dlt >= -128); s[n][e] = valid ? s[n][e] : -1e30f; }
;                 }
; #pragma unroll
;                 for (int n = 0; n < 4; ++n) mx = fmaxf(fmaxf(mx, fmaxf(s[n][0], s[n][1])), fmaxf(s[n][2], s[n][3]));
;                 mx = fmaxf(mx, __shfl_xor(mx, 16)); mx = fmaxf(mx, __shfl_xor(mx, 32));
;                 const float alpha = fexp(mrow[m] - mx); mrow[m] = mx; float ps = 0.f; const float mxl = mx * 1.4426950408889634f;
; #pragma unroll
;                 for (int n = 0; n < 4; ++n) {
;                     f32x4 pvv;
; #pragma unroll
;                     for (int e = 0; e < 4; ++e) { pvv[e] = __builtin_amdgcn_exp2f(s[n][e] * 1.4426950408889634f - mxl); ps += pvv[e]; }
;                     u32x2 w; w.x = cvt_pk_bf16(pvv[0], pvv[1]); w.y = cvt_pk_bf16(pvv[2], pvv[3]);
;                     *(LAS u32x2*)(Pl + (16 * m + fr) * 72 + 16 * n + 4 * fq) = w;
;                     o[m][n] = o[m][n] * alpha;
;                 }
;                 ps += __shfl_xor(ps, 16); ps += __shfl_xor(ps, 32);
;                 lrow[m] = lrow[m] * alpha + ps;
;             }
.LBB0_552:
	v_max_f32_e32 v175, v172, v173
	v_max_f32_e32 v193, v174, v192
	v_max3_f32 v175, v232, v175, v193
	v_max_f32_e32 v193, v168, v169
	v_max_f32_e32 v194, v170, v171
	v_max3_f32 v175, v175, v193, v194
	v_max_f32_e32 v193, v164, v165
	v_max_f32_e32 v194, v166, v167
	v_max3_f32 v175, v175, v193, v194
	v_max_f32_e32 v193, v160, v161
	v_max_f32_e32 v194, v162, v163
	v_max3_f32 v175, v175, v193, v194
	ds_bpermute_b32 v193, v222, v175
	v_add_u32_e32 v238, v205, v209
	s_andn2_b64 vcc, exec, s[12:13]
	s_waitcnt lgkmcnt(0)
	v_max_f32_e32 v175, v175, v193
	ds_bpermute_b32 v193, v223, v175
	s_waitcnt lgkmcnt(0)
	v_max_f32_e32 v193, v175, v193
	v_pk_mul_f32 v[194:195], v[192:193], s[6:7] op_sel_hi:[1,0]
	s_nop 0
	v_fma_f32 v172, v172, s6, -v195
	v_exp_f32_e32 v172, v172
	v_fma_f32 v173, v173, s6, -v195
	v_exp_f32_e32 v173, v173
	v_fma_f32 v174, v174, s6, -v195
	v_exp_f32_e32 v174, v174
	v_sub_f32_e32 v175, v194, v195
	v_exp_f32_e32 v175, v175
	v_fma_f32 v168, v168, s6, -v195
	v_add_f32_e32 v192, 0, v172
	v_exp_f32_e32 v168, v168
	v_fma_f32 v169, v169, s6, -v195
	v_fma_f32 v170, v170, s6, -v195
	v_fma_f32 v171, v171, s6, -v195
	v_add_f32_e32 v192, v173, v192
	v_exp_f32_e32 v169, v169
	v_exp_f32_e32 v170, v170
	v_exp_f32_e32 v171, v171
	v_add_f32_e32 v192, v174, v192
	v_add_f32_e32 v192, v175, v192
	v_cvt_pk_bf16_f32 v172, v172, v173
	v_cvt_pk_bf16_f32 v173, v174, v175
	v_add_f32_e32 v174, v168, v192
	v_add_f32_e32 v174, v169, v174
	v_cvt_pk_bf16_f32 v168, v168, v169
	v_cvt_pk_bf16_f32 v169, v170, v171
	v_add_u32_e32 v192, 0x9000, v238
	v_fma_f32 v164, v164, s6, -v195
	ds_write2_b64 v192, v[172:173], v[168:169] offset1:4
	v_exp_f32_e32 v168, v164
	v_fma_f32 v164, v165, s6, -v195
	v_exp_f32_e32 v169, v164
	v_fma_f32 v164, v166, s6, -v195
	v_add_f32_e32 v174, v170, v174
	v_exp_f32_e32 v170, v164
	v_fma_f32 v164, v167, s6, -v195
	v_add_f32_e32 v174, v171, v174
	v_exp_f32_e32 v171, v164
	v_fma_f32 v160, v160, s6, -v195
	v_add_f32_e32 v164, v168, v174
	v_exp_f32_e32 v194, v160
	v_fma_f32 v161, v161, s6, -v195
	v_add_f32_e32 v164, v169, v164
	v_exp_f32_e32 v234, v161
	v_fma_f32 v161, v162, s6, -v195
	v_add_f32_e32 v164, v170, v164
	v_exp_f32_e32 v237, v161
	v_fma_f32 v161, v163, s6, -v195
	v_add_f32_e32 v172, v171, v164
	v_mfma_f32_16x16x32_bf16 v[164:167], v[140:143], v[104:107], 0
	v_exp_f32_e32 v195, v161
	v_add_f32_e32 v160, v194, v172
	v_add_f32_e32 v160, v234, v160
	v_add_f32_e32 v160, v237, v160
	v_mfma_f32_16x16x32_bf16 v[172:175], v[132:135], v[108:111], v[164:167]
	v_add_f32_e32 v239, v195, v160
	ds_bpermute_b32 v240, v222, v239
	v_cvt_pk_bf16_f32 v196, v168, v169
	v_mfma_f32_16x16x32_bf16 v[164:167], v[156:159], v[104:107], 0
	v_cvt_pk_bf16_f32 v197, v170, v171
	v_cvt_pk_bf16_f32 v194, v194, v234
	v_cvt_pk_bf16_f32 v195, v237, v195
	v_mfma_f32_16x16x32_bf16 v[160:163], v[152:155], v[104:107], 0
	ds_write2_b64 v192, v[196:197], v[194:195] offset0:8 offset1:12
	s_waitcnt lgkmcnt(1)
	v_add_f32_e32 v192, v239, v240
	ds_bpermute_b32 v234, v223, v192
	v_mfma_f32_16x16x32_bf16 v[168:171], v[148:151], v[108:111], v[164:167]
	s_andn2_b64 s[2:3], exec, s[12:13]
	v_mfma_f32_16x16x32_bf16 v[164:167], v[144:147], v[108:111], v[160:163]
	v_mfma_f32_16x16x32_bf16 v[160:163], v[136:139], v[104:107], 0
	v_mfma_f32_16x16x32_bf16 v[160:163], v[128:131], v[108:111], v[160:163]
	s_cbranch_vccz .LBB0_554
	v_mov_b32_e32 v194, v175
	s_branch .LBB0_555
